# static s_setprio 1 for waves 4-7 held through the GEMM phases (set at gate/up tile-loop head, no reset after attention)
# baseline (speedup 1.0000x reference)
.LBB0_399:
	v_readfirstlane_b32 s100, v252
	s_nop 3
	s_cmpk_lt_u32 s100, 0x100
	s_cbranch_scc1 .Lgemm_prio_skip_a
	s_setprio 1
